# non-GEMM phases: unit index remapped (incl. strength-reduced u*256/u*128) so workgroups of one XCD process one batch, matching GEMM tile ownership
# speedup vs baseline: 1.0640x; 1.0640x over previous
; #define LAS __attribute__((address_space(3)))
; #define TID0() (wave0 * 64 + hw_lane())
; #define LAUNDER() int tp = TID0(); const int tid = tp, lane = tp & 63, wave = __builtin_amdgcn_readfirstlane(tp >> 6); (void)tid; (void)lane; (void)wave
; #define SEAM(k) do { if (lo <= (k) && (k) + 1 < hi) { XcdBarrier b2_ = bar; asm volatile("" : "+s"(b2_.bar)); xcd_barrier(b2_); } } while (0)
; __global__ void __launch_bounds__(512) fwd_kernel(Args a) {
;     ...
;     volatile LAS unsigned* bst = (volatile LAS unsigned*)(lds + 131072);
;     if (TID0() < 16) bst[TID0()] = 0u;
;     __syncthreads();
;     XcdBarrier bar = xcd_barrier_post((unsigned*)(a.ws + WS_BAR), bst);
;     unsigned char* ws = a.ws;
;     bf16* WIN = (bf16*)(ws + WS_WIN); bf16* WOUT = (bf16*)(ws + WS_WOUT); float* MODP = (float*)(ws + WS_MODP); float* DT = (float*)(ws + WS_DT);
;     float* TOT = (float*)(ws + WS_TOT); float* KMAX = (float*)(ws + WS_KMAX); bf16* WDT = (bf16*)(ws + WS_WDT); float* MODF = (float*)(ws + WS_MODF); float* LPA = (float*)(ws + WS_LPA); bf16* H = (bf16*)(ws + WS_H); bf16* YC = (bf16*)(ws + WS_YC); bf16* PROJ = (bf16*)(ws + WS_PROJ); float* STATES = (float*)(ws + WS_ST);
;     ...
;     if (IN(0) && EN_P0) { LAUNDER(); phase0(a.in[1], a.in[3], a.in[5], a.in[15], WIN, WOUT, MODP, KMAX, WDT, lds, tid, G); }
;     SEAM(0);
;     for (int l = 0; l < 2; ++l) {
;         const int pb = 1 + 6 * l;
;         const float* modp = MODP + (size_t)l * 8 * 8 * 3072; const float* adab = a.in[4] + l * 3072;
;         const float* xin = l == 0 ? a.in[0] : a.out;
;         const bool fusedp = (G == 256);
;         if (!(l == 1 && fusedp)) { if (IN(pb) && EN_P1) { LAUNDER(); phase_modulate(xin, a.in[2] + l * 1024, modp, adab, H, lds, tid, G, l == 0 ? MODF : nullptr, MODP, a.in[4]); }
;             SEAM(pb); }
;         if (IN(pb + 1) && EN_G1) { LAUNDER();
;             pg8::Gemm g{H, WIN + (size_t)l * NP * 1024, M, NP, 1024}; pg8::StaticOrder S; S.init(M, NP, G, (int)blockIdx.x);
;             pg8::EpiProj E{PROJ, (unsigned*)(KMAX + l * 1024), lds + 131072 + 1024};
.LBB0_89:
	s_add_u32 s0, s80, 0x1600000
	v_writelane_b32 v253, s68, 42
	s_addc_u32 s1, s81, 0
	s_add_u32 s70, s80, 0x1700000
	v_writelane_b32 v253, s69, 43
	v_writelane_b32 v253, s0, 44
	s_addc_u32 s71, s81, 0
	v_mov_b32_e32 v189, 0
	v_writelane_b32 v253, s1, 45
	s_add_u32 s0, s80, 0x1750000
	v_writelane_b32 v253, s0, 46
	s_addc_u32 s0, s81, 0
	v_writelane_b32 v253, s0, 47
	s_add_u32 s0, s80, 0x1580000
	s_addc_u32 s1, s81, 0
	s_add_u32 s96, s80, 0x16c0000
	s_addc_u32 s97, s81, 0
	s_add_u32 s6, s80, 0x1800000
	s_addc_u32 s7, s81, 0
	s_add_u32 s8, s80, 0xd800000
	s_addc_u32 s9, s81, 0
	s_add_u32 s10, s80, 0x3800000
	s_addc_u32 s11, s81, 0
	s_add_u32 s12, s80, 0xb800000
	s_addc_u32 s13, s81, 0
	v_writelane_b32 v253, s0, 48
	s_cmpk_eq_i32 s88, 0x100
	s_mov_b32 s84, 0x3f803f80
	v_writelane_b32 v253, s1, 49
	s_cselect_b64 s[0:1], -1, 0
	v_writelane_b32 v253, s0, 50
	s_cmpk_lg_i32 s88, 0x100
	v_mbcnt_lo_u32_b32 v0, -1, 0
	v_writelane_b32 v253, s1, 51
	s_cselect_b64 s[0:1], -1, 0
	v_writelane_b32 v253, s0, 52
	s_cmp_lg_u64 s[80:81], 0
	s_mov_b32 s35, 0
	v_writelane_b32 v253, s1, 53
	s_cselect_b64 s[0:1], -1, 0
	s_and_b32 s14, s66, 7
	s_lshl_b32 s14, s14, 5
	s_lshr_b32 s56, s66, 3
	s_or_b32 s14, s14, s56
	v_writelane_b32 v255, s14, 40
	s_lshl_b32 s14, s14, 9
	s_lshl_b32 s56, s88, 9
	v_writelane_b32 v253, s0, 54
	s_cmpk_lt_i32 s66, 0x100
	v_mov_b32_e32 v190, 0x358637bd
	v_writelane_b32 v253, s1, 55
	s_cselect_b64 s[0:1], -1, 0
	v_writelane_b32 v253, s0, 56
	s_cmp_eq_u32 s33, 15
	v_mov_b32_e32 v252, 1
	v_writelane_b32 v253, s1, 57
	s_cselect_b64 s[0:1], -1, 0
	v_writelane_b32 v253, s0, 58
	s_cmp_eq_u32 s33, 14
	v_mov_b32_e32 v226, 0x260
	v_writelane_b32 v253, s1, 59
	s_cselect_b64 s[0:1], -1, 0
	v_writelane_b32 v253, s0, 60
	s_cmp_eq_u32 s33, 13
	v_mov_b32_e32 v227, 0x3d4ccccd
	v_writelane_b32 v253, s1, 61
	s_cselect_b64 s[0:1], -1, 0
	v_writelane_b32 v253, s0, 62
	s_cmp_eq_u32 s33, 12
	s_mov_b32 s85, s84
	v_writelane_b32 v253, s1, 63
	s_cselect_b64 s[0:1], -1, 0
	v_writelane_b32 v254, s0, 0
	s_cmp_eq_u32 s33, 11
	s_mov_b32 s86, s84
	v_writelane_b32 v254, s1, 1
	s_cselect_b64 s[0:1], -1, 0
	v_writelane_b32 v254, s0, 2
	s_cmp_eq_u32 s33, 10
	s_mov_b32 s87, s84
	v_writelane_b32 v254, s1, 3
	s_cselect_b64 s[0:1], -1, 0
	v_writelane_b32 v254, s0, 4
	s_cmp_eq_u32 s33, 9
	v_mbcnt_hi_u32_b32 v224, -1, v0
	v_writelane_b32 v254, s1, 5
	s_cselect_b64 s[0:1], -1, 0
	v_writelane_b32 v254, s0, 6
	s_cmp_eq_u32 s33, 8
	v_mov_b32_e32 v192, 0x3f317218
	v_writelane_b32 v254, s1, 7
	s_cselect_b64 s[0:1], -1, 0
	v_writelane_b32 v254, s0, 8
	s_cmp_eq_u32 s33, 7
	v_mov_b32_e32 v233, 0x7ff
	v_writelane_b32 v254, s1, 9
	s_cselect_b64 s[0:1], -1, 0
	v_writelane_b32 v254, s0, 10
	s_cmp_eq_u32 s33, 6
	v_mov_b32_e32 v234, 0xf149f2ca
	v_writelane_b32 v254, s1, 11
	s_cselect_b64 s[0:1], -1, 0
	v_writelane_b32 v254, s0, 12
	s_cmp_eq_u32 s33, 5
	v_mov_b32_e32 v235, 0x70
	v_writelane_b32 v254, s1, 13
	s_cselect_b64 s[0:1], -1, 0
	v_writelane_b32 v254, s0, 14
	s_cmp_eq_u32 s33, 4
	v_mov_b32_e32 v236, 0x68
	v_writelane_b32 v254, s1, 15
	s_cselect_b64 s[0:1], -1, 0
	v_writelane_b32 v254, s0, 16
	s_cmp_eq_u32 s33, 3
	v_mov_b32_e32 v237, 0x60
	v_writelane_b32 v254, s1, 17
	s_cselect_b64 s[0:1], -1, 0
	v_writelane_b32 v254, s0, 18
	s_cmp_eq_u32 s33, 2
	v_mov_b32_e32 v238, 0x58
	v_writelane_b32 v254, s1, 19
	s_cselect_b64 s[0:1], -1, 0
	v_writelane_b32 v254, s0, 20
	s_cmp_eq_u32 s33, 1
	v_mov_b32_e32 v239, 0x50
	v_writelane_b32 v254, s1, 21
	s_cselect_b64 s[0:1], -1, 0
	v_writelane_b32 v254, s0, 22
	s_cmp_eq_u32 s33, 0
	v_mov_b32_e32 v240, 0x48
	v_writelane_b32 v254, s1, 23
	s_cselect_b64 s[0:1], -1, 0
	v_writelane_b32 v254, s0, 24
	v_mov_b32_e32 v241, 0x78
	v_mov_b32_e32 v0, v189
	v_writelane_b32 v254, s1, 25
	s_lshl_b32 s0, s33, 6
	s_cmpk_lt_i32 s66, 0x400
	v_writelane_b32 v254, s0, 26
	s_cselect_b64 s[0:1], -1, 0
	v_writelane_b32 v254, s0, 27
	s_ashr_i32 s5, s88, 31
	v_mov_b32_e32 v1, v189
	v_writelane_b32 v254, s1, 28
	s_ashr_i32 s0, s66, 31
	v_writelane_b32 v254, s0, 29
	s_lshr_b32 s0, s0, 29
	s_add_i32 s0, s66, s0
	s_ashr_i32 s4, s0, 3
	s_and_b32 s0, s0, -8
	s_sub_i32 s0, s66, s0
	s_lshl_b32 s1, s0, 7
	s_cmpk_lt_i32 s66, 0x200
	v_writelane_b32 v254, s5, 30
	s_cselect_b64 s[16:17], -1, 0
	v_writelane_b32 v254, s16, 31
	v_readlane_b32 s5, v253, 0
	s_add_i32 s5, s5, s14
	v_writelane_b32 v254, s17, 32
	v_writelane_b32 v254, s14, 33
	v_readlane_b32 s16, v253, 26
	v_writelane_b32 v254, s5, 34
	s_lshl_b32 s5, s0, 5
	v_readlane_b32 s20, v253, 30
	v_readlane_b32 s21, v253, 31
	s_add_u32 s14, s20, 0x1000
	s_addc_u32 s15, s21, 0
	v_writelane_b32 v254, s14, 35
	v_readlane_b32 s17, v253, 27
	v_readlane_b32 s18, v253, 28
	v_writelane_b32 v254, s15, 36
	s_add_u32 s14, s80, 0x1598000
	v_writelane_b32 v254, s14, 37
; #define LAUNDER() int tp = TID0(); const int tid = tp, lane = tp & 63, wave = __builtin_amdgcn_readfirstlane(tp >> 6); (void)tid; (void)lane; (void)wave
;     __host__ __device__ bool next(int i, Unit& u) const {
;         const long L = (long)i * G + c; if (L >= nwg) return false;
;         int wgid = (int)L; { const int q = nwg / NXCD, r = nwg % NXCD, xcd = wgid % NXCD, off = wgid / NXCD; wgid = (xcd < r ? xcd * (q + 1) : r * (q + 1) + (xcd - r) * q) + off; }
;         const int nig = WGM * nN, gid = wgid / nig, fm = gid * WGM, gsz = (nM - fm) < WGM ? (nM - fm) : WGM;
;         u.pm = fm + ((wgid % nig) % gsz); u.pn = (wgid % nig) / gsz; return true;
; __global__ void __launch_bounds__(512) fwd_kernel(Args a) {
;     ...
;         if (IN(pb + 1) && EN_G1) { LAUNDER();
;             pg8::Gemm g{H, WIN + (size_t)l * NP * 1024, M, NP, 1024}; pg8::StaticOrder S; S.init(M, NP, G, (int)blockIdx.x);
;             pg8::EpiProj E{PROJ, (unsigned*)(KMAX + l * 1024), lds + 131072 + 1024};
;             pg8::gemm_phase<pg8::EpiProj, pg8::StaticOrder, true, true>(lds, g, S, E, tp);
	s_addc_u32 s14, s81, 0
	v_writelane_b32 v254, s14, 38
	s_add_u32 s14, s80, 0x17a0000
	v_writelane_b32 v254, s14, 39
	s_addc_u32 s14, s81, 0
	v_writelane_b32 v254, s14, 40
	s_add_u32 s14, s80, 0x1784000
	v_writelane_b32 v254, s14, 41
	s_addc_u32 s14, s81, 0
	v_writelane_b32 v254, s14, 42
	s_add_u32 s14, s80, 0x1680000
	v_writelane_b32 v254, s14, 43
	s_addc_u32 s14, s81, 0
	v_writelane_b32 v254, s14, 44
	s_add_u32 s14, s80, 0x1784080
	v_writelane_b32 v254, s14, 45
	s_addc_u32 s14, s81, 0
	v_writelane_b32 v254, s14, 46
	s_cmp_lt_i32 s0, 0
	s_mul_i32 s14, s0, 0x81
	s_cselect_b32 s1, s14, s1
	s_mul_i32 s0, s0, 33
	s_cselect_b32 s5, s0, s5
	s_add_i32 s0, s1, s4
	s_ashr_i32 s1, s0, 31
	s_lshr_b32 s1, s1, 25
	s_add_i32 s1, s0, s1
	s_and_b32 s14, s1, 0xff80
	s_sub_i32 s0, s0, s14
	s_bfe_i32 s14, s0, 0x80000
	s_bfe_u32 s14, s14, 0x3000c
	s_add_i32 s14, s0, s14
	s_and_b32 s15, s14, 0xf8
	s_sub_i32 s0, s0, s15
	s_ashr_i32 s1, s1, 7
	s_bfe_i32 s14, s14, 0x80000
	s_lshl_b32 s1, s1, 3
	s_sext_i32_i16 s14, s14
	s_sext_i32_i8 s0, s0
	s_add_i32 s16, s1, s0
	s_ashr_i32 s0, s14, 3
	v_writelane_b32 v254, s0, 47
	s_lshr_b32 s0, s14, 3
	s_bfe_i64 s[0:1], s[0:1], 0x100000
	s_lshl_b64 s[0:1], s[0:1], 19
	v_writelane_b32 v254, s0, 48
	s_ashr_i32 s17, s16, 31
	v_readlane_b32 s22, v253, 32
	v_writelane_b32 v254, s1, 49
	s_mov_b32 s0, s16
	v_writelane_b32 v254, s0, 50
	v_readlane_b32 s23, v253, 33
	v_readlane_b32 s24, v253, 34
	v_writelane_b32 v254, s1, 51
	s_lshl_b64 s[0:1], s[16:17], 19
	s_add_u32 s0, s6, s0
	v_writelane_b32 v254, s6, 52
	s_addc_u32 s1, s7, s1
	v_readlane_b32 s25, v253, 35
	v_writelane_b32 v254, s7, 53
	s_add_u32 s6, s0, 0x40000
	v_writelane_b32 v254, s0, 54
	s_addc_u32 s7, s1, 0
	v_readlane_b32 s28, v253, 38
	v_writelane_b32 v254, s1, 55
	s_add_i32 s0, s5, s4
	s_ashr_i32 s1, s0, 31
	s_lshr_b32 s1, s1, 27
	s_add_i32 s1, s0, s1
	s_and_b32 s4, s1, 0xffe0
	s_sub_i32 s0, s0, s4
	s_bfe_i32 s4, s0, 0x80000
	s_bfe_u32 s4, s4, 0x3000c
	s_add_i32 s4, s0, s4
	s_and_b32 s5, s4, 0xf8
	s_sub_i32 s0, s0, s5
	s_ashr_i32 s1, s1, 5
	s_bfe_i32 s4, s4, 0x80000
	v_writelane_b32 v254, s6, 56
	s_lshl_b32 s1, s1, 3
	s_sext_i32_i16 s4, s4
	s_sext_i32_i8 s0, s0
	v_writelane_b32 v254, s7, 57
	s_add_i32 s6, s1, s0
	s_ashr_i32 s0, s4, 3
	v_writelane_b32 v254, s0, 58
	s_lshr_b32 s0, s4, 3
	s_bfe_i64 s[0:1], s[0:1], 0x100000
	s_lshl_b64 s[0:1], s[0:1], 19
	v_writelane_b32 v254, s0, 59
	s_ashr_i32 s7, s6, 31
	v_readlane_b32 s29, v253, 39
	v_writelane_b32 v254, s1, 60
	s_mov_b32 s0, s6
	v_writelane_b32 v254, s0, 61
	v_mov_b32_e32 v2, v189
	v_mov_b32_e32 v3, v189
	v_writelane_b32 v254, s1, 62
	s_lshl_b64 s[0:1], s[6:7], 19
	s_add_u32 s4, s8, s0
	s_mul_i32 s0, s89, s88
	s_addc_u32 s5, s9, s1
	s_mul_i32 s0, s0, s3
	v_writelane_b32 v254, s0, 63
	s_add_u32 s0, s4, 0x40000
	v_writelane_b32 v255, s4, 0
	s_addc_u32 s1, s5, 0
	s_ashr_i32 s57, s56, 31
	v_writelane_b32 v255, s5, 1
	v_writelane_b32 v255, s0, 2
	s_lshl_b64 s[90:91], s[56:57], 2
	s_movk_i32 s3, 0x3000
	v_writelane_b32 v255, s1, 3
	s_lshl_b32 s0, s2, 2
	s_and_b32 s0, s0, 0xffffff00
	s_add_i32 s0, s0, 0
	v_writelane_b32 v255, s0, 4
	s_add_u32 s0, s80, 0x6806000
	s_addc_u32 s1, s81, 0
	v_writelane_b32 v255, s0, 5
	s_mov_b32 s2, s56
	s_lshl_b32 s75, s88, 11
	v_writelane_b32 v255, s1, 6
	v_readlane_b32 s0, v255, 40
	s_lshl_b32 s0, s0, 8
	v_writelane_b32 v255, s0, 7
	s_lshl_b32 s0, s88, 8
	v_writelane_b32 v255, s0, 8
	v_readlane_b32 s0, v255, 40
	s_lshl_b32 s0, s0, 7
	v_writelane_b32 v255, s0, 9
	s_lshl_b32 s0, s88, 7
	v_writelane_b32 v255, s0, 10
	s_add_i32 s0, 0, 0x20000
	v_writelane_b32 v255, s0, 11
	s_add_i32 s0, 0, 0x20004
	v_writelane_b32 v255, s0, 12
	s_add_i32 s0, 0, 0x1a800
	v_writelane_b32 v255, s0, 13
	s_add_i32 s0, 0, 0x8800
	v_writelane_b32 v255, s0, 14
	s_add_i32 s0, 0, 0x19800
	v_writelane_b32 v255, s0, 15
	s_add_i32 s0, 0, 0x19a00
	v_writelane_b32 v255, s0, 16
	s_add_i32 s0, 0, 0x19c00
	v_writelane_b32 v255, s0, 17
	s_add_i32 s0, 0, 0x19e00
	v_writelane_b32 v255, s0, 18
	v_writelane_b32 v255, s96, 19
	s_movk_i32 s73, 0x81
	s_mov_b32 s89, 0x2aaaaaab
	v_writelane_b32 v255, s97, 20
	v_writelane_b32 v255, s2, 21
	s_movk_i32 s24, 0x800
	s_movk_i32 s25, 0x1ff
	v_writelane_b32 v255, s3, 22
	v_writelane_b32 v255, s90, 23
	s_mov_b32 s15, 0x800000
	s_mov_b32 s92, 0xf800000
	v_writelane_b32 v255, s91, 24
	s_movk_i32 s93, 0x810
	s_movk_i32 s14, 0x801
	s_movk_i32 s22, 0x201
	s_movk_i32 s23, 0x7f8
	s_movk_i32 s17, 0x7f4
	s_movk_i32 s72, 0x4400
	s_mov_b32 s74, 0x5040100
	s_mov_b64 s[0:1], 0
	s_mov_b64 s[28:29], 0x80
	s_mov_b64 s[6:7], 0x100
	s_mov_b32 s18, s35
	v_writelane_b32 v255, s75, 25
	v_readlane_b32 s19, v253, 29
	v_readlane_b32 s26, v253, 36
	v_readlane_b32 s27, v253, 37
	v_readlane_b32 s30, v253, 40
	v_readlane_b32 s31, v253, 41
	s_branch .LBB0_93

; #define LAS __attribute__((address_space(3)))
; DI void phase_modulate(const float* xin, const float* norm_w, const float* modp, const float* adab,
;                        bf16* H, LAS unsigned char* lds, int tid, int G, float* MODF, const float* MODP_all, const float* adab_all) {
;     const int lane = tid & 63, wave = tid >> 6;
;     if (MODF) for (int idx = blockIdx.x * 512 + tid; idx < 2 * 8 * 3072; idx += G * 512) { const int l2 = idx / 24576, rem = idx - l2 * 24576, b2 = rem / 3072, c2 = rem - b2 * 3072;
;         float v = adab_all[l2 * 3072 + c2];
; #pragma unroll
;         for (int ks = 0; ks < 8; ++ks) v += MODP_all[((size_t)(l2 * 8 + ks) * 8 + b2) * 3072 + c2];
;         MODF[idx] = v; }
;     LAS float* sh = (LAS float*)lds; LAS float* sc = sh + 1024;
;     __syncthreads();
;     f32x4 nw[4];
; #pragma unroll
;     for (int j = 0; j < 4; ++j) nw[j] = *(const f32x4*)(norm_w + 4 * lane + 256 * j);
;     int curb = -1;
;     for (int rb = blockIdx.x; rb < 256; rb += G) {
;         const int b = rb >> 5;
;         if (b != curb) {
;             __syncthreads();
;             for (int i = tid; i < 2048; i += 512) { float v = adab[i];
; #pragma unroll
;                 for (int ks = 0; ks < 8; ++ks) v += modp[(size_t)(ks * 8 + b) * 3072 + i];
;                 sh[i] = (i >= 1024) ? 1.f + v : v; }
;             curb = b; __syncthreads();
;         }
;         f32x4 vbuf[3][4];
; #pragma unroll
;         for (int pre = 0; pre < 2; ++pre) { const f32x4* xr = (const f32x4*)(xin + (size_t)(rb * 64 + wave + 8 * pre) * 1024) + lane;
; #pragma unroll
;             for (int j = 0; j < 4; ++j) vbuf[pre][j] = __builtin_nontemporal_load(xr + 64 * j); }
.LBB0_98:
	s_or_b64 exec, exec, s[0:1]
	v_readlane_b32 s0, v253, 56
	v_readlane_b32 s1, v253, 57
	s_movk_i32 s56, 0x3ff
	s_andn2_b64 vcc, exec, s[0:1]
	s_barrier
	s_cbranch_vccnz .LBB0_111
	v_readlane_b32 s4, v255, 27
	s_lshl_b32 s34, s4, 10
	v_readlane_b32 s36, v253, 26
	s_lshl_b64 s[0:1], s[34:35], 2
	v_readlane_b32 s40, v253, 30
	v_readlane_b32 s41, v253, 31
	s_add_u32 s0, s40, s0
	v_and_b32_e32 v21, 63, v20
	s_addc_u32 s1, s41, s1
	v_lshlrev_b32_e32 v188, 4, v21
	s_waitcnt lgkmcnt(0)
	global_load_dwordx4 v[4:7], v188, s[0:1]
	global_load_dwordx4 v[8:11], v188, s[0:1] offset:1024
	global_load_dwordx4 v[12:15], v188, s[0:1] offset:2048
	global_load_dwordx4 v[16:19], v188, s[0:1] offset:3072
	v_and_b32_e32 v22, 64, v224
	v_add_u32_e32 v22, 64, v22
	v_xor_b32_e32 v23, 1, v224
	v_cmp_lt_i32_e32 vcc, v23, v22
	s_mul_i32 s2, s4, 0xc0000
	s_add_u32 s26, s58, s2
	v_cndmask_b32_e32 v23, v224, v23, vcc
	v_lshlrev_b32_e32 v91, 2, v23
	v_xor_b32_e32 v23, 2, v224
	v_cmp_lt_i32_e32 vcc, v23, v22
	s_mul_i32 s34, s4, 0xc00
	v_readlane_b32 s44, v253, 34
	v_cndmask_b32_e32 v23, v224, v23, vcc
	v_lshlrev_b32_e32 v92, 2, v23
	v_xor_b32_e32 v23, 4, v224
	v_cmp_lt_i32_e32 vcc, v23, v22
	s_addc_u32 s27, s59, 0
	s_lshl_b64 s[0:1], s[34:35], 2
	v_cndmask_b32_e32 v23, v224, v23, vcc
	v_lshlrev_b32_e32 v93, 2, v23
	v_xor_b32_e32 v23, 8, v224
	v_cmp_lt_i32_e32 vcc, v23, v22
	v_readlane_b32 s45, v253, 35
	s_add_u32 s30, s44, s0
	v_cndmask_b32_e32 v23, v224, v23, vcc
	v_lshlrev_b32_e32 v94, 2, v23
	v_xor_b32_e32 v23, 16, v224
	v_cmp_lt_i32_e32 vcc, v23, v22
	s_addc_u32 s31, s45, s1
	v_readlane_b32 s0, v254, 52
	v_cndmask_b32_e32 v23, v224, v23, vcc
	v_lshlrev_b32_e32 v95, 2, v23
	v_xor_b32_e32 v23, 32, v224
	v_cmp_lt_i32_e32 vcc, v23, v22
	v_lshl_add_u64 v[78:79], s[18:19], 0, v[188:189]
	v_add_u32_e32 v97, 0, v188
	v_cndmask_b32_e32 v22, v224, v23, vcc
	v_lshlrev_b32_e32 v96, 2, v22
	v_max_i32_e32 v22, 0x600, v76
	v_sub_u32_e32 v22, v22, v76
	v_add_u32_e32 v22, 0x1ff, v22
	v_lshrrev_b32_e32 v23, 9, v22
	v_add_u32_e32 v23, 1, v23
	v_lshlrev_b32_e32 v188, 3, v21
	v_readlane_b32 s1, v254, 53
	v_readlane_b32 s5, v255, 28
	v_readlane_b32 s37, v253, 27
	v_readlane_b32 s38, v253, 28
	v_readlane_b32 s39, v253, 29
	v_and_b32_e32 v98, 0xfffffe, v23
	v_lshl_add_u64 v[80:81], s[0:1], 0, v[188:189]
	v_readlane_b32 s0, v255, 4
	s_add_u32 s2, s80, s2
	v_ashrrev_i32_e32 v90, 6, v76
	v_cmp_gt_i32_e64 s[36:37], s24, v76
	s_mov_b32 s16, -1
	v_cmp_lt_u32_e64 s[38:39], s25, v22
	v_lshl_add_u32 v99, v98, 9, v76
	v_add_u32_e32 v77, 0x200, v76
	v_cmp_ne_u32_e64 s[40:41], v23, v98
	v_lshl_add_u32 v100, v20, 2, s0
	s_addc_u32 s4, s81, 0
	v_readlane_b32 s5, v255, 40
	s_nop 4
	v_readlane_b32 s42, v253, 32
	v_readlane_b32 s43, v253, 33
	v_readlane_b32 s46, v253, 36
	v_readlane_b32 s47, v253, 37
	v_readlane_b32 s48, v253, 38
	v_readlane_b32 s49, v253, 39
	v_readlane_b32 s50, v253, 40
	v_readlane_b32 s51, v253, 41
	s_branch .LBB0_102

; DI void mixerB2_unit(int u, int l, const bf16* PROJ, bf16* YC, const float* dlam_l, const float* dnw_l, const float* kmax_l, LAS char* lds, int tid, int wave, int lane) {
;     const int b = u >> 5, h = (u >> 3) & 3, qb = u & 7, r = lane & 15, g = lane >> 4, q = (lane & 15) >> 2, p = lane & 3;
;     const bf16* kbase = slab(PROJ, C_BK + h * 64, b); const bf16* vbase = slab(PROJ, C_BV + h * 64, b);
;     const bf16* qbase = slab(PROJ, C_BQ + h * 64, b); const bf16* gbase = slab(PROJ, C_BG + h * 64, b);
;     const int q0w = qb * 256 + wave * 32;
;     LAS char* Kb = lds; LAS char* Vb = lds + 2 * KV_TILE;
;     const float slope2 = ex2(-(float)(2 * h + 2)) * LOG2E;
;     __syncthreads();
;     bf16x8 q1[2], q2[2]; float bound[2];
;     LAS char* qs = lds + 92160 + wave * (32 * KV_PITCH);
; #pragma unroll
;     for (int qt = 0; qt < 2; ++qt) { const bf16* qp = qbase + (size_t)(q0w + 16 * qt + r) * 64 + 8 * g;
;         q1[qt] = *(const bf16x8*)qp; q2[qt] = *(const bf16x8*)(qp + 32);
;         *(LAS bf16x8*)(qs + (16 * qt + r) * KV_PITCH + 16 * g) = q1[qt]; *(LAS bf16x8*)(qs + (16 * qt + r) * KV_PITCH + 64 + 16 * g) = q2[qt]; }
;     const int lrow = tid >> 3, lch = tid & 7;
;     u32x4 rk = *(const u32x4*)(kbase + (size_t)lrow * 64 + lch * 8), rv = *(const u32x4*)(vbase + (size_t)lrow * 64 + lch * 8);
;     u32x4 rk2 = *(const u32x4*)(kbase + (size_t)(lrow + 64) * 64 + lch * 8), rv2 = *(const u32x4*)(vbase + (size_t)(lrow + 64) * 64 + lch * 8);
;     *(LAS u32x4*)(Kb + lrow * KV_PITCH + lch * 16) = rk; *(LAS u32x4*)(Vb + lrow * KV_PITCH + lch * 16) = rv;
;     *(LAS u32x4*)(Kb + (lrow + 64) * KV_PITCH + lch * 16) = rk2; *(LAS u32x4*)(Vb + (lrow + 64) * KV_PITCH + lch * 16) = rv2;
;     __syncthreads();
;     { const float k1 = kmax_l[b * 128 + 40 + 2 * h], k2 = kmax_l[b * 128 + 41 + 2 * h];
; #pragma unroll
;       for (int qt = 0; qt < 2; ++qt) { float a = sumsq8(q1[qt]), c = sumsq8(q2[qt]);
;           a += __shfl_xor(a, 16); a += __shfl_xor(a, 32); c += __shfl_xor(c, 16); c += __shfl_xor(c, 32);
;           bound[qt] = fmaxf(sqrtf(a * k1), sqrtf(c * k2)) * 1.01f + 0.05f; } }
;     f32x4 Pf;
; #pragma unroll
;     for (int i = 0; i < 4; ++i) Pf[i] = (float)(4 * g + i - r);
;     const float nslope2s = __builtin_bit_cast(float, __builtin_amdgcn_readfirstlane(__builtin_bit_cast(int, -slope2)));
;     float nbound[2] = {-bound[0], -bound[1]};
.Lmx_b_go:
	v_readlane_b32 s0, v253, 0
	v_mbcnt_lo_u32_b32 v4, -1, 0
	v_mbcnt_hi_u32_b32 v4, -1, v4
	v_readlane_b32 s56, v255, 8
	s_waitcnt lgkmcnt(0)
	v_add_u32_e32 v5, s0, v4
	v_readlane_b32 s0, v253, 56
	v_readlane_b32 s1, v253, 57
	s_andn2_b64 vcc, exec, s[0:1]
	s_nop 0
	v_cndmask_b32_e64 v6, 0, 1, s[0:1]
	v_cmp_ne_u32_e64 s[36:37], 1, v6
	v_readfirstlane_b32 s0, v5
	s_cbranch_vccnz .LBB0_262
	v_readlane_b32 s60, v255, 27
	s_lshl_b32 s34, s60, 7
	v_readlane_b32 s40, v253, 26
	s_ashr_i32 s16, s0, 6
	s_lshl_b64 s[0:1], s[34:35], 2
	v_readlane_b32 s52, v253, 38
	v_readlane_b32 s53, v253, 39
	s_add_u32 s20, s52, s0
	s_addc_u32 s21, s53, s1
	s_lshl_b32 s34, s60, 6
	v_readlane_b32 s54, v253, 40
	s_lshl_b64 s[0:1], s[34:35], 2
	v_readlane_b32 s55, v253, 41
	s_add_u32 s0, s54, s0
	s_addc_u32 s1, s55, s1
	s_lshl_b32 s34, s60, 10
	s_lshl_b64 s[4:5], s[34:35], 2
	v_readlane_b32 s26, v253, 42
	v_readlane_b32 s27, v253, 43
	s_add_u32 s2, s26, s4
	s_mul_i32 s26, s16, 0x1200
	s_addc_u32 s4, s27, s5
	s_add_i32 s26, s26, 0
	s_add_i32 s26, s26, 0x16800
	v_and_b32_e32 v165, 15, v4
	v_mov_b32_e32 v6, s26
	s_movk_i32 s30, 0x90
	v_mad_u32_u24 v13, v165, s30, v6
	v_ashrrev_i32_e32 v6, 3, v5
	v_and_b32_e32 v5, 7, v4
	v_mul_lo_u32 v14, v6, s30
	v_lshlrev_b32_e32 v15, 4, v5
	v_add3_u32 v182, 0, v14, v15
	v_and_b32_e32 v14, 64, v224
	v_lshlrev_b32_e32 v170, 3, v5
	v_xor_b32_e32 v5, 16, v224
	v_add_u32_e32 v14, 64, v14
	v_cmp_lt_i32_e32 vcc, v5, v14
	v_bfe_u32 v11, v4, 4, 2
	v_bfe_u32 v12, v4, 2, 2
	v_cndmask_b32_e32 v5, v224, v5, vcc
	v_lshlrev_b32_e32 v184, 2, v5
	v_xor_b32_e32 v5, 32, v224
	v_cmp_lt_i32_e32 vcc, v5, v14
	v_lshlrev_b32_e32 v164, 3, v11
	v_and_b32_e32 v10, 63, v4
	v_cndmask_b32_e32 v5, v224, v5, vcc
	v_lshlrev_b32_e32 v185, 2, v5
	v_lshlrev_b32_e32 v5, 2, v11
	v_sub_u32_e32 v11, v5, v165
	v_or_b32_e32 v5, v5, v12
	v_mul_u32_u24_e32 v198, 0x90, v5
	v_lshlrev_b32_e32 v5, 3, v4
	v_and_b32_e32 v199, 24, v5
	v_or_b32_e32 v5, 48, v10
	v_mul_u32_u24_e32 v200, 0x90, v5
	v_xor_b32_e32 v5, 1, v224
	v_cmp_lt_i32_e32 vcc, v5, v14
	v_cmp_gt_u32_e64 s[38:39], 32, v10
	v_lshlrev_b32_e32 v188, 2, v10
	v_cndmask_b32_e32 v5, v224, v5, vcc
	v_lshlrev_b32_e32 v201, 2, v5
	v_xor_b32_e32 v5, 2, v224
	v_cvt_f32_u32_e32 v10, s60
	v_cmp_lt_i32_e32 vcc, v5, v14
	s_lshl_b32 s5, s16, 5
	s_mulk_i32 s16, 0x900
	v_cndmask_b32_e32 v5, v224, v5, vcc
	v_lshlrev_b32_e32 v202, 2, v5
	v_xor_b32_e32 v5, 4, v224
	v_cmp_lt_i32_e32 vcc, v5, v14
	v_mul_f32_e32 v10, 0xbe99999a, v10
	v_mul_f32_e32 v10, 0x3fb8aa3b, v10
	v_cndmask_b32_e32 v5, v224, v5, vcc
	v_lshlrev_b32_e32 v203, 2, v5
	v_xor_b32_e32 v5, 8, v224
	v_exp_f32_e32 v10, v10
	v_add_u32_e32 v16, 1, v11
	v_cmp_lt_i32_e32 vcc, v5, v14
	s_add_i32 s16, s16, 0
	v_cvt_f32_i32_e32 v186, v11
	v_cvt_f32_i32_e32 v187, v16
	v_add_u32_e32 v16, 2, v11
	v_add_u32_e32 v11, 3, v11
	v_cndmask_b32_e32 v5, v224, v5, vcc
	s_add_i32 s16, s16, 0x12000
	v_and_b32_e32 v166, 48, v4
	v_ashrrev_i32_e32 v7, 31, v6
	v_cvt_f32_i32_e32 v191, v16
	v_cvt_f32_i32_e32 v193, v11
	v_lshlrev_b32_e32 v204, 2, v5
	v_mov_b32_e32 v5, 0x3f4ccccd
	v_bfe_u32 v207, v4, 3, 3
	v_mov_b32_e32 v4, s16
	v_mov_b32_e32 v167, v189
	v_lshlrev_b64 v[168:169], 6, v[6:7]
	s_mov_b64 s[26:27], 0x1000
	v_fmamk_f32 v205, v10, 0xbf19999a, v5
	v_mad_u32_u24 v12, v165, s30, v4
	v_lshl_add_u64 v[174:175], s[0:1], 0, v[166:167]
	v_lshlrev_b64 v[4:5], 7, v[6:7]
	v_readlane_b32 s0, v255, 5
	v_lshl_add_u64 v[8:9], v[168:169], 0, s[26:27]
	v_add_u32_e32 v10, s16, v15
	v_mul_u32_u24_e32 v11, 0x90, v207
	v_or_b32_e32 v14, 32, v164
	v_or_b32_e32 v16, 64, v164
	v_or_b32_e32 v17, 0x60, v164
	v_or_b32_e32 v4, v4, v15
	v_readlane_b32 s1, v255, 6
	v_mul_u32_u24_e32 v171, 0x90, v165
	v_add_u32_e32 v183, 0x2400, v182
	v_lshl_add_u64 v[172:173], s[20:21], 0, v[188:189]
	v_sub_f32_e32 v206, 1.0, v205
	v_or_b32_e32 v208, 8, v207
	v_lshl_add_u64 v[176:177], s[0:1], 0, v[4:5]
	s_sub_i32 s16, 0, s5
	v_add_u32_e32 v167, v10, v11
	v_add_u32_e32 v209, v12, v164
	v_add_u32_e32 v210, v12, v14
	v_add_u32_e32 v211, v12, v16
	v_add_u32_e32 v212, v12, v17
	v_add_u32_e32 v213, v13, v166
	v_lshlrev_b64 v[178:179], 1, v[8:9]
	v_readlane_b32 s30, v255, 7
	v_readlane_b32 s31, v255, 40
	s_nop 4
	v_readlane_b32 s61, v255, 28
	v_readlane_b32 s41, v253, 27
	v_readlane_b32 s42, v253, 28
	v_readlane_b32 s43, v253, 29
	v_readlane_b32 s44, v253, 30
	v_readlane_b32 s45, v253, 31
	v_readlane_b32 s46, v253, 32
	v_readlane_b32 s47, v253, 33
	v_readlane_b32 s48, v253, 34
	v_readlane_b32 s49, v253, 35
	v_readlane_b32 s50, v253, 36
	v_readlane_b32 s51, v253, 37
	s_branch .LBB0_252

; #define LAS __attribute__((address_space(3)))
; DI void ssd_part1_unit(int u, const bf16* PROJ, float* DT, const bf16* H, const bf16* wdtb_l, const float* dt_bias_l, const float* cw, const float* cb, const float* a_log_l, float* STATES, float* TOT,
;                        LAS unsigned char* ldsu, int tid, int wave, int lane) {
;     const int b = u >> 5, c = (u >> 1) & 15, grp = u & 1, t0 = c * 128;
;     LAS char* lds = (LAS char*)ldsu;
;     LAS char* XS = lds; LAS char* BM = lds + IMG_BYTES;
;     LAS float* gtab = (LAS float*)(lds + 3 * IMG_BYTES); LAS float* wtab = gtab + 512;
;     const int r = lane & 15, g = lane >> 4, q = (lane & 15) >> 2, p = lane & 3;
;     __syncthreads();
;     {
;         LAS char* wl = lds + 3 * IMG_BYTES + 4096;
;         LAS char* hst = lds + 2 * IMG_BYTES + wave * (16 * IMG_PITCH);
;         for (int i = tid; i < 1024; i += 512) { const int row = i >> 7, ch = i & 127; *(LAS u32x4*)(wl + row * 2064 + ch * 16) = *(const u32x4*)(wdtb_l + (size_t)row * 1024 + ch * 8); }
;         __syncthreads();
;         f32x4 dacc = {0.f, 0.f, 0.f, 0.f};
;         const bf16* hrow = H + (size_t)(b * T + t0 + 16 * wave) * 1024;
;         u32x4 hv[4];
; #pragma unroll
;         for (int it = 0; it < 4; ++it) { const int n = lane + 64 * it; hv[it] = __builtin_nontemporal_load((const u32x4*)(hrow + (size_t)(n >> 4) * 1024 + (n & 15) * 8)); }
;         for (int ck = 0; ck < 8; ++ck) {
.Lmx_s1_go:
	v_readlane_b32 s0, v253, 0
	s_waitcnt vmcnt(0)
	s_barrier
	v_mbcnt_lo_u32_b32 v4, -1, 0
	v_mbcnt_hi_u32_b32 v4, -1, v4
	s_and_b64 vcc, exec, s[36:37]
	v_add_u32_e32 v103, s0, v4
	v_readlane_b32 s56, v255, 10
	v_readfirstlane_b32 s0, v103
	s_barrier
	s_cbranch_vccnz .LBB0_356
	v_readlane_b32 s30, v255, 27
	s_lshl_b32 s34, s30, 3
	v_readlane_b32 s44, v253, 5
	s_ashr_i32 s1, s0, 6
	s_lshl_b64 s[4:5], s[34:35], 2
	v_readlane_b32 s50, v253, 11
	v_readlane_b32 s51, v253, 12
	s_add_u32 s40, s50, s4
	s_mul_i32 s34, s30, 0xf00
	s_addc_u32 s41, s51, s5
	s_lshl_b64 s[20:21], s[34:35], 2
	v_readlane_b32 s45, v253, 6
	s_add_u32 s20, s44, s20
	s_mul_i32 s34, s30, 0x300
	v_readlane_b32 s46, v253, 7
	s_addc_u32 s21, s45, s21
	s_lshl_b64 s[26:27], s[34:35], 2
	v_readlane_b32 s47, v253, 8
	s_add_u32 s26, s46, s26
	v_readlane_b32 s48, v253, 9
	s_addc_u32 s27, s47, s27
	v_readlane_b32 s49, v253, 10
	s_add_u32 s2, s48, s4
	s_addc_u32 s4, s49, s5
	s_mul_i32 s5, s1, 0x1100
	s_add_i32 s5, s5, 0
	s_movk_i32 s16, 0x400
	s_add_i32 s5, s5, 0x11000
	v_cmp_gt_i32_e64 s[36:37], s16, v103
	s_lshl_b32 s16, s30, 15
	v_readlane_b32 s30, v253, 46
	v_readlane_b32 s31, v255, 28
	s_add_u32 s30, s30, s16
	v_readlane_b32 s16, v253, 47
	v_lshlrev_b32_e32 v6, 4, v103
	s_addc_u32 s31, s16, 0
	v_and_b32_e32 v188, 0x7f0, v6
	v_readlane_b32 s16, v255, 13
	v_lshlrev_b32_e32 v8, 4, v4
	v_lshl_add_u64 v[100:101], s[30:31], 0, v[188:189]
	v_add_u32_e32 v102, s16, v188
	v_and_b32_e32 v188, 0xf0, v8
	v_and_b32_e32 v7, 15, v4
	s_lshl_b32 s30, s1, 4
	v_readlane_b32 s38, v254, 52
	v_add_u32_e32 v13, s5, v188
	v_mov_b32_e32 v14, s5
	s_movk_i32 s5, 0x110
	v_readlane_b32 s39, v254, 53
	v_mad_u32_u24 v15, v7, s5, v14
	v_mov_b32_e32 v14, s16
	v_readlane_b32 s5, v255, 14
	s_cmp_lt_i32 s1, 4
	v_lshl_add_u64 v[104:105], s[38:39], 0, v[188:189]
	v_mad_u32_u24 v19, v7, s93, v14
	v_lshlrev_b32_e32 v188, 2, v7
	v_mov_b32_e32 v14, s5
	s_movk_i32 s5, 0x100
	s_cselect_b64 s[96:97], -1, 0
	s_and_b32 s16, s1, 1
	v_lshl_add_u64 v[106:107], s[40:41], 0, v[188:189]
	v_readlane_b32 s42, v253, 44
	v_cmp_gt_u32_e64 s[40:41], s5, v103
	s_ashr_i32 s5, s0, 7
	s_lshl_b32 s33, s16, 2
	s_lshl_b32 s0, s16, 4
	v_and_b32_e32 v5, 63, v4
	v_readlane_b32 s43, v253, 45
	s_add_u32 s94, s42, s0
	v_readlane_b32 s52, v253, 13
	v_readlane_b32 s53, v253, 14
	v_lshlrev_b32_e32 v11, 3, v5
	s_addc_u32 s95, s43, 0
	v_readlane_b32 s54, v253, 15
	v_readlane_b32 s55, v253, 16
	v_lshl_add_u64 v[108:109], s[42:43], 0, v[188:189]
	v_lshlrev_b32_e32 v110, 1, v5
	v_cmp_eq_u32_e64 s[42:43], 0, v5
	v_cmp_gt_u32_e64 s[44:45], 2, v5
	v_cmp_gt_u32_e64 s[46:47], 4, v5
	v_cmp_gt_u32_e64 s[48:49], 8, v5
	v_cmp_gt_u32_e64 s[50:51], 16, v5
	v_cmp_gt_u32_e64 s[52:53], 32, v5
	s_cmp_eq_u32 s16, 0
	v_lshl_or_b32 v5, s1, 9, v11
	v_readlane_b32 s0, v255, 15
	s_cselect_b64 s[54:55], -1, 0
	s_lshl_b32 s1, s1, 5
	v_add_u32_e32 v229, s0, v5
	s_add_i32 s0, 0, 0x1a000
	v_bfe_u32 v9, v4, 4, 2
	v_lshlrev_b32_e32 v6, 6, v4
	v_and_b32_e32 v17, 48, v4
	v_add_u32_e32 v230, s0, v5
	v_bfe_u32 v4, v4, 2, 2
	s_add_i32 s1, s1, 0
	v_and_b32_e32 v5, 24, v11
	s_ashr_i32 s31, s30, 31
	v_cndmask_b32_e64 v16, v14, 0, s[40:41]
	v_lshrrev_b32_e32 v14, 1, v103
	v_add_u32_e32 v11, s1, v5
	v_lshl_or_b32 v4, v9, 3, v4
	v_lshl_add_u32 v231, v9, 5, s0
	s_lshl_b64 s[0:1], s[30:31], 2
	v_readlane_b32 s58, v253, 19
	v_readlane_b32 s59, v253, 20
	v_and_b32_e32 v6, 0xc00, v6
	v_lshlrev_b32_e32 v191, 3, v7
	v_and_b32_e32 v225, 0x78, v14
	v_mul_u32_u24_e32 v25, 0x110, v4
	v_lshlrev_b32_e32 v4, 9, v9
	s_add_u32 s0, s12, s0
	v_readlane_b32 s56, v253, 17
	v_readlane_b32 s58, v253, 24
	v_or_b32_e32 v8, 0x1000, v6
	v_or_b32_e32 v10, 0x2000, v6
	v_or_b32_e32 v12, 0x3000, v6
	v_cmp_gt_u32_e64 s[38:39], 8, v7
	v_mul_u32_u24_e32 v21, 0x110, v9
	v_and_b32_e32 v14, 56, v191
	v_lshl_add_u32 v7, v7, 4, v16
	v_mul_u32_u24_e32 v23, 0x110, v225
	s_addc_u32 s1, s13, s1
	v_or_b32_e32 v16, 0x1800, v4
	v_or_b32_e32 v18, 0x800, v4
	v_or_b32_e32 v20, 0x880, v4
	v_or_b32_e32 v22, 0x900, v4
	v_or_b32_e32 v24, 0x980, v4
	v_or_b32_e32 v26, 0x1000, v4
	v_or_b32_e32 v28, 0x1080, v4
	v_or_b32_e32 v30, 0x1100, v4
	v_or_b32_e32 v32, 0x1180, v4
	v_or_b32_e32 v34, 0x1880, v4
	v_or_b32_e32 v36, 0x1900, v4
	v_or_b32_e32 v38, 0x1980, v4
	v_readlane_b32 s59, v253, 25
	v_readlane_b32 s56, v255, 10
	v_lshlrev_b32_e32 v111, 2, v9
	v_add_u32_e32 v228, -2, v225
	v_lshl_add_u64 v[112:113], s[0:1], 0, v[188:189]
	v_add3_u32 v232, 0, v5, v25
	v_lshlrev_b32_e32 v114, 1, v6
	v_lshlrev_b32_e32 v188, 1, v8
	v_lshlrev_b32_e32 v116, 1, v10
	v_lshlrev_b32_e32 v118, 1, v12
	v_lshlrev_b32_e32 v120, 1, v14
	v_add_u32_e32 v242, v7, v23
	v_add_u32_e32 v243, v11, v25
	v_lshlrev_b32_e32 v122, 2, v4
	v_lshlrev_b32_e32 v124, 2, v18
	v_lshlrev_b32_e32 v126, 2, v20
	v_lshlrev_b32_e32 v128, 2, v22
	v_lshlrev_b32_e32 v130, 2, v24
	v_lshlrev_b32_e32 v132, 2, v26
	v_lshlrev_b32_e32 v134, 2, v28
	v_lshlrev_b32_e32 v136, 2, v30
	v_lshlrev_b32_e32 v138, 2, v32
	v_lshlrev_b32_e32 v140, 2, v16
	v_lshlrev_b32_e32 v142, 2, v34
	v_lshlrev_b32_e32 v144, 2, v36
	v_lshlrev_b32_e32 v146, 2, v38
	v_add_u32_e32 v244, v13, v21
	v_add_u32_e32 v245, v15, v17
	v_add_u32_e32 v246, v19, v17
	v_readlane_b32 s31, v255, 40
	s_nop 4
	v_readlane_b32 s57, v253, 18
	s_branch .LBB0_266

; #define LAS __attribute__((address_space(3)))
; DI float ex2(float x) { return __builtin_amdgcn_exp2f(x); }
; DI float a_bound(const bf16x8 (&qf)[2], const float* kmax_l, int b, int h) { return sqrtf(q_norm2(qf) * (kmax_l[b * 128 + 8 + 2 * h] + kmax_l[b * 128 + 9 + 2 * h])) * 1.01f + 0.05f; }
; DI void mixerA1_unit(int u, const bf16* PROJ, bf16* YC, float* LPA, const float* kmax_l, LAS char* vt, int wave, int lane) {
;     const int b = u >> 6, h = (u >> 4) & 3, qblk = u & 15, r = lane & 15, g = lane >> 4;
;     const bf16* kb = slab(PROJ, C_AK + h * 64, b); const bf16* vb = slab(PROJ, C_AV + h * 64, b);
;     const int t0 = qblk * 128 + wave * 16, tq = t0 + r;
;     bf16x8 qf[2];
; #pragma unroll
;     for (int ks = 0; ks < 2; ++ks) qf[ks] = *(const bf16x8*)(slab(PROJ, C_AQ + h * 64, b) + (size_t)tq * 64 + 32 * ks + 8 * g);
;     const float nslope2 = -ex2(-(float)(2 * h + 1)) * LOG2E;
;     const float bound = a_bound(qf, kmax_l, b, h);
;     const f32x4 cinit = {-bound, -bound, -bound, -bound};
;     f32x4 o[4], ol = {0.f, 0.f, 0.f, 0.f};
; #pragma unroll
;     for (int c = 0; c < 4; ++c) o[c] = ol;
;     TileRegs R0, R1, R2;
;     const int tb0 = t0 - 64;
.LBB0_356:
	v_readlane_b32 s0, v253, 0
	v_readlane_b32 s4, v254, 31
	s_waitcnt vmcnt(63) expcnt(7) lgkmcnt(15)
	s_barrier
	v_mbcnt_lo_u32_b32 v4, -1, 0
	v_mbcnt_hi_u32_b32 v4, -1, v4
	v_readlane_b32 s5, v254, 32
	v_add_u32_e32 v5, s0, v4
	v_readlane_b32 s94, v255, 33
	v_readfirstlane_b32 s0, v5
	v_cndmask_b32_e64 v5, 0, 1, s[4:5]
	v_readlane_b32 s96, v255, 19
	v_cmp_ne_u32_e64 s[36:37], 1, v5
	s_andn2_b64 vcc, exec, s[4:5]
	v_readlane_b32 s95, v255, 34
	v_readlane_b32 s97, v255, 20
	s_cbranch_vccnz .LBB0_361
	s_ashr_i32 s5, s0, 6
	s_lshl_b32 s0, s5, 14
	s_add_i32 s16, s0, 0
	v_readlane_b32 s0, v255, 27
	v_readlane_b32 s1, v255, 28
	s_lshl_b32 s34, s0, 10
	s_lshl_b64 s[0:1], s[34:35], 2
	v_readlane_b32 s20, v253, 42
	v_bfe_u32 v7, v4, 4, 2
	s_add_u32 s2, s20, s0
	v_and_b32_e32 v109, 15, v4
	v_lshlrev_b32_e32 v131, 2, v7
	v_mov_b32_e32 v10, s16
	s_movk_i32 s0, 0x90
	v_bfe_u32 v11, v4, 2, 4
	v_mad_u32_u24 v132, v109, s0, v10
	v_mad_u32_u24 v10, v11, s0, v10
	v_sub_u32_e32 v11, v131, v109
	v_add_u32_e32 v12, 1, v11
	v_and_b32_e32 v8, 64, v224
	v_cvt_f32_i32_e32 v134, v12
	v_add_u32_e32 v12, 2, v11
	v_xor_b32_e32 v6, 16, v224
	v_add_u32_e32 v8, 64, v8
	v_cvt_f32_i32_e32 v135, v12
	v_add_u32_e32 v12, 3, v11
	v_cmp_lt_i32_e32 vcc, v6, v8
	v_cvt_f32_i32_e32 v136, v12
	v_add_u32_e32 v12, 16, v11
	v_cndmask_b32_e32 v6, v224, v6, vcc
	v_cvt_f32_u32_e32 v137, v12
	v_add_u32_e32 v12, 17, v11
	v_lshlrev_b32_e32 v124, 2, v6
	v_xor_b32_e32 v6, 32, v224
	v_cvt_f32_i32_e32 v133, v11
	v_cvt_f32_u32_e32 v138, v12
	v_add_u32_e32 v12, 18, v11
	v_add_u32_e32 v11, 19, v11
	v_and_b32_e32 v5, 63, v4
	v_cmp_lt_i32_e32 vcc, v6, v8
	v_bfe_u32 v126, v4, 3, 3
	v_lshlrev_b32_e32 v9, 4, v4
	v_cvt_f32_u32_e32 v139, v12
	v_cvt_f32_u32_e32 v140, v11
	v_lshlrev_b32_e32 v108, 3, v7
	v_cndmask_b32_e32 v6, v224, v6, vcc
	v_lshlrev_b32_e32 v8, 3, v5
	v_or_b32_e32 v127, 8, v126
	v_and_b32_e32 v9, 0x70, v9
	v_and_b32_e32 v7, 48, v4
	v_and_b32_e32 v4, 7, v4
	v_readlane_b32 s21, v253, 43
	v_lshlrev_b32_e32 v125, 2, v6
	v_and_b32_e32 v6, 56, v8
	v_add_u32_e32 v9, s16, v9
	v_mul_u32_u24_e32 v130, 0x90, v126
	v_and_b32_e32 v8, 24, v8
	v_lshl_add_u32 v141, v4, 4, s16
	v_lshlrev_b32_e32 v4, 3, v4
	v_mul_u32_u24_e32 v11, 0x90, v127
	s_addc_u32 s4, s21, s1
	s_lshl_b32 s5, s5, 4
	v_or_b32_e32 v128, 16, v126
	v_or_b32_e32 v129, 24, v126
	v_cmp_gt_u32_e32 vcc, 16, v5
	v_lshlrev_b32_e32 v110, 1, v6
	v_add_u32_e32 v142, v9, v130
	v_add_u32_e32 v143, v132, v7
	v_add_u32_e32 v144, v10, v8
	v_lshlrev_b32_e32 v112, 1, v4
	v_add_u32_e32 v145, v141, v11
	v_readlane_b32 s16, v255, 9
	v_readlane_b32 s26, v255, 40
	s_nop 4
	s_branch .LBB0_359

; #define LAS __attribute__((address_space(3)))
; DI float q_norm2(const bf16x8 (&qf)[2]) { float a = sumsq8(qf[0]) + sumsq8(qf[1]); a += __shfl_xor(a, 16); a += __shfl_xor(a, 32); return a; }
; DI void mixerD2_unit(int u, const bf16* PROJ, bf16* YC, float rmax, const float* kmax_l, LAS char* vt, int wave, int lane) {
;     const int b = u >> 6, h = (u >> 4) & 3, wu = (u & 15) * 8 + wave, rr = wu >> 2, cb = wu & 3, r = lane & 15, g = lane >> 4;
;     const bf16* kb = slab(PROJ, C_DK + h * 64, b); const bf16* vb = slab(PROJ, C_DV + h * 64, b);
;     const int qcol = 16 * cb + r, tq = 64 * rr + qcol;
;     const int cs = min(max(qcol - 8, 0), 48), rs = min(max(rr - 4, 0), 24), c0 = min(max(16 * cb - 8, 0), 32);
;     LAS float* rp = (LAS float*)(vt + 12288);
;     bf16x8 qf[2];
; #pragma unroll
;     for (int ks = 0; ks < 2; ++ks) qf[ks] = *(const bf16x8*)(slab(PROJ, C_DQ + h * 64, b) + (size_t)tq * 64 + 32 * ks + 8 * g);
;     const float bound = sqrtf(q_norm2(qf) * (kmax_l[b * 128 + 104 + 2 * h] + kmax_l[b * 128 + 105 + 2 * h])) * 1.01f + 0.05f + rmax;
;     const f32x4 cinit = {-bound, -bound, -bound, -bound};
;     f32x4 o[4], ol = {0.f, 0.f, 0.f, 0.f};
; #pragma unroll
;     for (int c = 0; c < 4; ++c) o[c] = ol;
;     const int tb0 = 64 * rs + c0, dr0 = rs - rr + 7;
;     const int kc0 = c0 + 4 * g - cs;
;     const LAS float* rpl = rp + dr0 * 31 + (c0 + 4 * g - qcol + 15);
;     TileRegs R0, R1, R2;
.LBB0_361:
	v_readlane_b32 s0, v253, 0
	v_mbcnt_lo_u32_b32 v4, -1, 0
	v_mbcnt_hi_u32_b32 v4, -1, v4
	s_and_b64 vcc, exec, s[36:37]
	s_nop 0
	v_add_u32_e32 v5, s0, v4
	s_nop 0
	v_readfirstlane_b32 s0, v5
	s_cbranch_vccnz .LBB0_369
	s_ashr_i32 s2, s0, 6
	v_readlane_b32 s26, v255, 27
	v_readlane_b32 s1, v254, 26
	s_lshl_b32 s0, s2, 14
	s_lshl_b32 s34, s26, 10
	s_add_i32 s20, s0, 0
	s_lshl_b64 s[0:1], s[34:35], 2
	v_readlane_b32 s4, v253, 42
	v_readlane_b32 s5, v253, 43
	s_add_u32 s4, s4, s0
	s_addc_u32 s5, s5, s1
	s_lshl_b32 s0, s2, 4
	s_and_b32 s16, s0, 48
	v_and_b32_e32 v5, 15, v4
	v_sub_u32_e64 v8, s16, 8 clamp
	v_or_b32_e32 v78, s16, v5
	v_readfirstlane_b32 s0, v8
	v_bfe_u32 v6, v4, 4, 2
	v_sub_u32_e64 v7, v78, 8 clamp
	v_and_b32_e32 v10, 64, v224
	s_min_u32 s33, s0, 32
	v_lshlrev_b32_e32 v68, 3, v6
	v_xor_b32_e32 v9, 16, v224
	v_add_u32_e32 v10, 64, v10
	v_min_u32_e32 v7, 48, v7
	v_lshl_add_u32 v6, v6, 2, s33
	v_cmp_lt_i32_e32 vcc, v9, v10
	v_sub_u32_e32 v7, v6, v7
	v_mov_b32_e32 v8, s20
	s_movk_i32 s1, 0x90
	v_cndmask_b32_e32 v9, v224, v9, vcc
	v_mad_u32_u24 v87, v5, s1, v8
	v_add_u32_e32 v5, 1, v7
	v_lshlrev_b32_e32 v79, 2, v9
	v_xor_b32_e32 v9, 32, v224
	v_cmp_gt_u32_e64 s[38:39], 16, v5
	v_add_u32_e32 v5, 2, v7
	v_cmp_lt_i32_e32 vcc, v9, v10
	v_cmp_gt_u32_e64 s[40:41], 16, v5
	v_add_u32_e32 v5, 3, v7
	v_and_b32_e32 v69, 63, v4
	v_cndmask_b32_e32 v9, v224, v9, vcc
	v_cmp_gt_u32_e64 s[42:43], 16, v5
	v_add_u32_e32 v5, 17, v7
	v_lshlrev_b32_e32 v80, 2, v9
	v_sub_u32_e32 v6, v6, v78
	v_lshlrev_b32_e32 v9, 3, v69
	s_movk_i32 s0, 0xffef
	v_cmp_gt_u32_e64 s[46:47], 16, v5
	v_add_u32_e32 v5, 18, v7
	v_lshl_add_u32 v81, v6, 2, s20
	v_and_b32_e32 v6, 56, v9
	v_cmp_gt_u32_e64 s[36:37], 16, v7
	v_cmp_lt_u32_e64 s[44:45], s0, v7
	v_cmp_gt_u32_e64 s[48:49], 16, v5
	v_add_u32_e32 v5, 19, v7
	v_and_b32_e32 v7, 24, v9
	v_xor_b32_e32 v9, 1, v224
	v_cmp_lt_i32_e32 vcc, v9, v10
	v_lshlrev_b32_e32 v11, 4, v4
	v_cmp_gt_u32_e64 s[50:51], 16, v5
	v_cndmask_b32_e32 v9, v224, v9, vcc
	v_lshlrev_b32_e32 v89, 2, v9
	v_xor_b32_e32 v9, 2, v224
	v_cmp_lt_i32_e32 vcc, v9, v10
	v_bfe_u32 v5, v4, 2, 4
	v_bfe_u32 v82, v4, 3, 3
	v_cndmask_b32_e32 v9, v224, v9, vcc
	v_lshlrev_b32_e32 v90, 2, v9
	v_xor_b32_e32 v9, 4, v224
	v_cmp_lt_i32_e32 vcc, v9, v10
	v_and_b32_e32 v11, 0x70, v11
	v_mad_u32_u24 v5, v5, s1, v8
	v_cndmask_b32_e32 v9, v224, v9, vcc
	v_and_b32_e32 v8, 7, v4
	v_lshlrev_b32_e32 v91, 2, v9
	v_xor_b32_e32 v9, 8, v224
	v_readlane_b32 s52, v253, 5
	v_or_b32_e32 v83, 8, v82
	v_add_u32_e32 v11, s20, v11
	v_lshl_add_u32 v88, v8, 4, s20
	v_cmp_lt_i32_e32 vcc, v9, v10
	s_addk_i32 s20, 0x3000
	s_mul_i32 s1, s26, 0x1d10
	v_readlane_b32 s64, v253, 17
	v_readlane_b32 s66, v253, 19
	v_mul_u32_u24_e32 v86, 0x90, v82
	v_and_b32_e32 v12, 48, v4
	v_lshlrev_b32_e32 v4, 3, v8
	v_mul_u32_u24_e32 v8, 0x90, v83
	v_cndmask_b32_e32 v9, v224, v9, vcc
	v_lshl_add_u32 v93, v69, 2, s20
	s_mul_hi_u32 s0, s26, 0x1d10
	v_readlane_b32 s65, v253, 18
	v_readlane_b32 s66, v253, 23
	s_add_u32 s20, s64, s1
	s_mov_b32 s34, -1
	v_or_b32_e32 v84, 16, v82
	v_or_b32_e32 v85, 24, v82
	v_lshlrev_b32_e32 v92, 2, v9
	v_or_b32_e32 v94, 0xffffffc0, v69
	s_addc_u32 s21, s65, s0
	v_mov_b32_e32 v99, 0
	v_lshlrev_b32_e32 v70, 1, v6
	v_add_u32_e32 v95, v11, v86
	v_add_u32_e32 v96, v87, v12
	v_add_u32_e32 v97, v5, v7
	v_lshlrev_b32_e32 v72, 1, v4
	v_add_u32_e32 v98, v88, v8
	v_readlane_b32 s52, v255, 40
	s_nop 4
	v_readlane_b32 s27, v255, 28
	v_readlane_b32 s53, v253, 6
	v_readlane_b32 s54, v253, 7
	v_readlane_b32 s55, v253, 8
	v_readlane_b32 s56, v253, 9
	v_readlane_b32 s57, v253, 10
	v_readlane_b32 s58, v253, 11
	v_readlane_b32 s59, v253, 12
	v_readlane_b32 s60, v253, 13
	v_readlane_b32 s61, v253, 14
	v_readlane_b32 s62, v253, 15
	v_readlane_b32 s63, v253, 16
	v_readlane_b32 s67, v253, 20
	s_branch .LBB0_364

; #define LAS __attribute__((address_space(3)))
; DI float ex2(float x) { return __builtin_amdgcn_exp2f(x); }
; DI float a_bound(const bf16x8 (&qf)[2], const float* kmax_l, int b, int h) { return sqrtf(q_norm2(qf) * (kmax_l[b * 128 + 8 + 2 * h] + kmax_l[b * 128 + 9 + 2 * h])) * 1.01f + 0.05f; }
; #define A_LOAD(R, t_) do { int tb_, sd_, md_; a_desc((t_), a0, rho, tb_, sd_, md_); tile_load(R, kb, vb, tb_, sd_, lane); } while (0)
; DI void mixerA2_unit(int u, const bf16* PROJ, bf16* YC, const float* LPA, const float* kmax_l, LAS char* vt, int wave, int lane) {
;     const int b = u >> 6, h = (u >> 4) & 3, rho = u & 15, a0 = 16 * wave, r = lane & 15, g = lane >> 4;
;     const bf16* kb = slab(PROJ, C_AK + h * 64, b); const bf16* vb = slab(PROJ, C_AV + h * 64, b);
;     const int tq = 16 * (a0 + r) + rho;
;     bf16x8 qf[2];
; #pragma unroll
;     for (int ks = 0; ks < 2; ++ks) qf[ks] = *(const bf16x8*)(slab(PROJ, C_AQ + h * 64, b) + (size_t)tq * 64 + 32 * ks + 8 * g);
;     const float nslope2 = -ex2(-(float)(2 * h + 1)) * LOG2E;
;     const float bound = a_bound(qf, kmax_l, b, h);
;     const f32x4 cinit = {-bound, -bound, -bound, -bound};
;     f32x4 o[4], ol = {0.f, 0.f, 0.f, 0.f};
; #pragma unroll
;     for (int c = 0; c < 4; ++c) o[c] = ol;
;     TileRegs R0, R1, R2;
;     ...
;     A_LOAD(R0, 0); A_LOAD(R1, 1); A_LOAD(R2, 2);
;     f32x4 sA[2], sB[2];
.Lsw_a2:
	v_readlane_b32 s0, v253, 0
	v_mbcnt_lo_u32_b32 v4, -1, 0
	v_mbcnt_hi_u32_b32 v4, -1, v4
	s_waitcnt lgkmcnt(0)
	s_nop 0
	v_add_u32_e32 v5, s0, v4
	v_readlane_b32 s0, v254, 31
	v_readlane_b32 s1, v254, 32
	s_andn2_b64 vcc, exec, s[0:1]
	v_readfirstlane_b32 s0, v5
	s_cbranch_vccnz .LBB0_423
	v_writelane_b32 v255, s26, 35
	s_ashr_i32 s2, s0, 6
	s_lshl_b32 s0, s2, 14
	v_writelane_b32 v255, s27, 36
	s_add_i32 s4, s0, 0
	v_readlane_b32 s0, v255, 27
	v_readlane_b32 s1, v255, 28
	s_lshl_b32 s34, s0, 10
	s_lshl_b64 s[0:1], s[34:35], 2
	v_readlane_b32 s20, v253, 42
	v_readlane_b32 s21, v253, 43
	s_add_u32 s60, s20, s0
	s_addc_u32 s61, s21, s1
	v_and_b32_e32 v7, 15, v4
	v_bfe_u32 v8, v4, 4, 2
	s_lshl_b32 s62, s2, 8
	v_lshl_or_b32 v149, v7, 4, s62
	v_lshlrev_b32_e32 v167, 6, v8
	v_lshlrev_b32_e32 v148, 3, v8
	v_sub_u32_e32 v8, v167, v149
	v_mov_b32_e32 v14, s4
	s_movk_i32 s0, 0x90
	v_mad_u32_u24 v169, v7, s0, v14
	v_add_u32_e32 v7, 0x400, v8
	v_cmp_gt_u32_e64 s[36:37], s14, v7
	v_add_u32_e32 v7, 16, v8
	v_cvt_f32_i32_e32 v171, v7
	v_add_u32_e32 v7, 32, v8
	v_and_b32_e32 v9, 64, v224
	v_add_u32_e32 v15, 0x410, v8
	v_cvt_f32_i32_e32 v172, v7
	v_add_u32_e32 v7, 48, v8
	s_add_i32 s63, s62, 0xffffff00
	s_add_i32 s64, s62, 0xffffff80
	v_xor_b32_e32 v6, 16, v224
	v_add_u32_e32 v9, 64, v9
	v_cmp_gt_u32_e64 s[38:39], s14, v15
	v_add_u32_e32 v15, 0x420, v8
	v_cvt_f32_i32_e32 v173, v7
	v_add_u32_e32 v7, 0x100, v8
	s_cmpk_lt_u32 s63, 0x800
	v_cmp_lt_i32_e32 vcc, v6, v9
	v_cmp_gt_u32_e64 s[40:41], s14, v15
	v_add_u32_e32 v15, 0x430, v8
	v_cvt_f32_i32_e32 v174, v7
	v_add_u32_e32 v7, 0x110, v8
	s_cselect_b64 s[54:55], -1, 0
	s_cmpk_lt_u32 s64, 0x800
	v_cndmask_b32_e32 v6, v224, v6, vcc
	v_cmp_gt_u32_e64 s[42:43], s14, v15
	v_add_u32_e32 v15, 0x500, v8
	v_cvt_f32_i32_e32 v175, v7
	v_add_u32_e32 v7, 0x120, v8
	s_cselect_b64 s[90:91], -1, 0
	s_add_i32 s65, s62, 0x100
	v_lshlrev_b32_e32 v160, 2, v6
	v_xor_b32_e32 v6, 32, v224
	v_cmp_gt_u32_e64 s[44:45], s14, v15
	v_add_u32_e32 v15, 0x510, v8
	v_cvt_f32_i32_e32 v176, v7
	v_add_u32_e32 v7, 0x130, v8
	s_cmpk_lt_u32 s62, 0x800
	v_and_b32_e32 v5, 63, v4
	v_cmp_lt_i32_e32 vcc, v6, v9
	v_bfe_u32 v9, v4, 3, 3
	v_lshlrev_b32_e32 v13, 4, v4
	v_cvt_f32_i32_e32 v170, v8
	v_cmp_gt_u32_e64 s[46:47], s14, v15
	v_add_u32_e32 v15, 0x520, v8
	v_add_u32_e32 v8, 0x530, v8
	v_cvt_f32_i32_e32 v177, v7
	s_cselect_b64 s[20:21], -1, 0
	s_add_i32 s68, s62, 0x180
	v_cndmask_b32_e32 v6, v224, v6, vcc
	v_lshlrev_b32_e32 v5, 3, v5
	v_or_b32_e32 v10, 8, v9
	v_and_b32_e32 v13, 0x70, v13
	v_cmp_gt_u32_e64 s[50:51], s14, v8
	v_bfe_u32 v7, v4, 2, 4
	s_cmpk_lt_u32 s65, 0x800
	v_and_b32_e32 v8, 7, v4
	v_lshlrev_b32_e32 v161, 2, v6
	v_and_b32_e32 v6, 56, v5
	v_or_b32_e32 v11, 16, v9
	v_or_b32_e32 v12, 24, v9
	v_add_u32_e32 v13, s4, v13
	v_mul_u32_u24_e32 v166, 0x90, v9
	v_and_b32_e32 v168, 48, v4
	v_mad_u32_u24 v7, v7, s0, v14
	v_and_b32_e32 v5, 24, v5
	s_mov_b64 s[56:57], s[96:97]
	s_cselect_b64 s[96:97], -1, 0
	s_cmpk_lt_u32 s68, 0x800
	v_lshlrev_b32_e32 v4, 3, v8
	v_lshl_add_u32 v182, v8, 4, s4
	v_mul_u32_u24_e32 v8, 0x90, v10
	v_lshlrev_b32_e32 v162, 4, v9
	v_lshlrev_b32_e32 v163, 4, v10
	v_lshlrev_b32_e32 v164, 4, v11
	v_lshlrev_b32_e32 v165, 4, v12
	v_cmp_gt_u32_e64 s[48:49], s14, v15
	v_lshlrev_b32_e32 v178, 2, v9
	v_lshlrev_b32_e32 v179, 2, v10
	v_lshlrev_b32_e32 v180, 2, v11
	v_lshlrev_b32_e32 v181, 2, v12
	s_cselect_b64 s[26:27], -1, 0
	v_lshlrev_b32_e32 v150, 1, v6
	v_add_u32_e32 v183, v13, v166
	v_add_u32_e32 v184, v7, v5
	v_lshlrev_b32_e32 v152, 1, v4
	v_add_u32_e32 v185, v182, v8
	v_readlane_b32 s69, v255, 40
	s_nop 4
	s_movk_i32 s58, 0x7bc
	s_movk_i32 s67, 0x7fc
	s_movk_i32 s59, 0x7b8
	s_movk_i32 s52, 0x7b4

; #define LAS __attribute__((address_space(3)))
; DI unsigned pk2(float lo, float hi) { f32x2_t v = {lo, hi}; bf16x2_t b = __builtin_convertvector(v, bf16x2_t); return __builtin_bit_cast(unsigned, b); }
; DI void ssd_part2_unit(int u, const bf16* PROJ, const float* DT, const float* cw, const float* cb, const float* a_log_l, const float* dskip_l, const float* snw_l,
;                        const float* STATES, bf16* YC, LAS unsigned char* ldsu, int tid, int wave, int lane) {
;     const int b = u >> 5, c = (u >> 1) & 15, grp = u & 1, t0 = c * 128;
;     LAS char* lds = (LAS char*)ldsu;
;     LAS char* XS = lds; LAS char* BM = lds + IMG_BYTES; LAS char* CM = lds + 2 * IMG_BYTES;
;     LAS float* gtab = (LAS float*)(lds + 3 * IMG_BYTES); LAS float* dttab = gtab + 512;
;     __syncthreads();
;     if (tid < 256) conv_image(CM, PROJ, b, t0, 512 + grp * 128, cw, cb, tid);
;     if (wave >= 4) decay_tables<false>(gtab, dttab, DT, a_log_l, nullptr, b, c, grp, wave - 4, lane);
; #pragma unroll 4
;     for (int k = 0; k < 16; ++k) { const int idx = tid + 512 * k, combo = idx >> 11, within = idx & 2047, pp = within >> 5, n4 = within & 31;
;         const int hh = combo >> 1, dir = combo & 1, h = 2 * grp + hh;
;         const f32x4 sv = *(const f32x4*)(STATES + ((size_t)(((b * 16 + c) * 4 + h) * 2 + dir) * 64 + pp) * 128 + n4 * 4);
;         u32x2 w; w.x = pk2(sv[0], sv[1]); w.y = pk2(sv[2], sv[3]);
;         *(LAS u32x2*)(lds + combo * (64 * IMG_PITCH) + pp * IMG_PITCH + n4 * 8) = w; }
;     __syncthreads();
;     const int r = lane & 15, g = lane >> 4, q = (lane & 15) >> 2, p = lane & 3;
;     const int l0 = 16 * wave, lq = l0 + r;
;     bf16x8 cq[4];
; #pragma unroll
;     for (int ks = 0; ks < 4; ++ks) cq[ks] = *(const LAS bf16x8*)(CM + lq * IMG_PITCH + 64 * ks + 16 * g);
;     f32x4 acc[2][4];
.LBB0_469:
	s_cmp_le_i32 s82, s2
	s_cselect_b64 s[20:21], -1, 0
	s_and_b64 s[0:1], s[20:21], s[0:1]
	s_andn2_b64 vcc, exec, s[0:1]
	s_cbranch_vccnz .LBB0_524
	v_readlane_b32 s0, v253, 0
	v_mbcnt_lo_u32_b32 v4, -1, 0
	v_mbcnt_hi_u32_b32 v4, -1, v4
	v_mov_b32_e32 v195, 1
	s_movk_i32 s56, 0x2000
	v_add_u32_e32 v193, s0, v4
	v_readlane_b32 s0, v253, 56
	v_readlane_b32 s1, v253, 57
	s_andn2_b64 vcc, exec, s[0:1]
	v_readfirstlane_b32 s0, v193
	s_cbranch_vccnz .LBB0_523
	v_readlane_b32 s4, v255, 27
	s_mul_i32 s34, s4, 0xf00
	s_ashr_i32 s2, s0, 6
	s_lshl_b64 s[0:1], s[34:35], 2
	v_readlane_b32 s36, v253, 5
	v_readlane_b32 s37, v253, 6
	s_add_u32 s26, s36, s0
	s_mul_i32 s34, s4, 0x300
	v_readlane_b32 s38, v253, 7
	s_addc_u32 s27, s37, s1
	s_lshl_b64 s[0:1], s[34:35], 2
	v_readlane_b32 s39, v253, 8
	s_add_u32 s52, s38, s0
	s_addc_u32 s53, s39, s1
	s_lshl_b32 s34, s4, 3
	v_readlane_b32 s40, v253, 9
	s_lshl_b64 s[0:1], s[34:35], 2
	v_readlane_b32 s41, v253, 10
	s_add_u32 s68, s40, s0
	s_addc_u32 s69, s41, s1
	s_lshl_b32 s34, s4, 2
	v_readlane_b32 s44, v253, 13
	s_lshl_b64 s[0:1], s[34:35], 2
	v_readlane_b32 s45, v253, 14
	s_add_u32 s54, s44, s0
	s_addc_u32 s55, s45, s1
	s_lshl_b32 s34, s4, 8
	v_readlane_b32 s46, v253, 15
	s_lshl_b64 s[0:1], s[34:35], 2
	v_readlane_b32 s47, v253, 16
	s_add_u32 s90, s46, s0
	s_movk_i32 s0, 0x100
	s_addc_u32 s91, s47, s1
	v_cmp_gt_i32_e64 s[36:37], s0, v193
	s_add_i32 s0, 0, 0x11000
	v_readlane_b32 s5, v255, 28
	s_cmp_gt_i32 s2, 3
	s_cselect_b64 s[96:97], -1, 0
	s_add_i32 s1, s2, -4
	s_and_b32 s5, s2, 1
	s_lshr_b32 s33, s1, 1
	s_lshl_b32 s4, s5, 2
	s_lshl_b32 s16, s5, 4
	v_readlane_b32 s30, v253, 44
	v_readlane_b32 s31, v253, 45
	s_add_u32 s30, s30, s16
	v_ashrrev_i32_e32 v6, 1, v193
	s_addc_u32 s31, s31, 0
	s_waitcnt lgkmcnt(0)
	v_and_b32_e32 v5, 63, v4
	v_readlane_b32 s42, v253, 11
	v_readlane_b32 s43, v253, 12
	v_readlane_b32 s48, v253, 17
	v_readlane_b32 s49, v253, 18
	v_readlane_b32 s50, v253, 19
	v_readlane_b32 s51, v253, 20
	v_and_b32_e32 v203, -8, v6
	s_movk_i32 s34, 0x110
	v_or_b32_e32 v6, 7, v6
	s_cmp_eq_u32 s5, 0
	v_and_b32_e32 v7, 15, v4
	v_mul_lo_u32 v11, v6, s34
	v_lshlrev_b32_e32 v200, 1, v5
	v_cmp_eq_u32_e64 s[38:39], 0, v5
	v_cmp_gt_u32_e64 s[40:41], 2, v5
	v_cmp_gt_u32_e64 s[42:43], 4, v5
	v_cmp_gt_u32_e64 s[44:45], 8, v5
	v_cmp_gt_u32_e64 s[46:47], 16, v5
	v_cmp_gt_u32_e64 s[48:49], 32, v5
	s_cselect_b64 s[50:51], -1, 0
	v_lshlrev_b32_e32 v6, 3, v5
	s_lshl_b32 s5, s2, 4
	v_or_b32_e32 v5, 48, v5
	v_lshlrev_b32_e32 v199, 3, v7
	v_lshlrev_b32_e32 v8, 4, v7
	v_or_b32_e32 v202, s5, v7
	v_mul_u32_u24_e32 v216, 0x110, v7
	v_mul_u32_u24_e32 v7, 0x110, v5
	v_lshrrev_b32_e32 v5, 8, v193
	v_mul_i32_i24_e32 v5, 0x8800, v5
	v_add_u32_e32 v9, s0, v8
	v_and_b32_e32 v12, 31, v4
	v_and_b32_e32 v213, 48, v4
	v_add3_u32 v8, 0, v5, v8
	v_bfe_u32 v17, v4, 2, 4
	v_lshlrev_b32_e32 v4, 3, v4
	v_and_b32_e32 v5, 64, v224
	v_and_b32_e32 v18, 24, v4
	v_xor_b32_e32 v4, 16, v224
	v_add_u32_e32 v19, 64, v5
	v_cmp_lt_i32_e32 vcc, v4, v19
	v_mul_lo_u32 v13, v202, s34
	v_add_u32_e32 v14, s0, v13
	v_cndmask_b32_e32 v4, v224, v4, vcc
	v_lshlrev_b32_e32 v223, 2, v4
	v_xor_b32_e32 v4, 32, v224
	v_cmp_lt_i32_e32 vcc, v4, v19
	s_movk_i32 s0, 0xff00
	v_lshlrev_b32_e32 v15, 2, v202
	v_cndmask_b32_e32 v4, v224, v4, vcc
	v_lshlrev_b32_e32 v242, 2, v4
	v_add_u32_e32 v4, -1, v224
	v_cmp_lt_i32_e32 vcc, v4, v5
	v_and_or_b32 v217, v193, s0, v199
	v_readlane_b32 s0, v255, 16
	v_cndmask_b32_e32 v4, v4, v224, vcc
	v_lshlrev_b32_e32 v243, 2, v4
	v_add_u32_e32 v4, -2, v224
	v_cmp_lt_i32_e32 vcc, v4, v5
	v_bfe_u32 v19, v193, 5, 6
	v_lshrrev_b32_e32 v16, 1, v193
	v_cndmask_b32_e32 v4, v4, v224, vcc
	v_lshlrev_b32_e32 v244, 2, v4
	v_add_u32_e32 v4, -4, v224
	v_cmp_lt_i32_e32 vcc, v4, v5
	v_add_u32_e32 v220, s0, v15
	v_readlane_b32 s0, v255, 17
	v_cndmask_b32_e32 v4, v4, v224, vcc
	v_lshlrev_b32_e32 v245, 2, v4
	v_add_u32_e32 v4, -8, v224
	v_cmp_lt_i32_e32 vcc, v4, v5
	v_lshlrev_b32_e32 v188, 9, v19
	v_lshl_or_b32 v6, s1, 9, v6
	v_cndmask_b32_e32 v4, v4, v224, vcc
	v_lshlrev_b32_e32 v246, 2, v4
	v_add_u32_e32 v4, -16, v224
	v_cmp_lt_i32_e32 vcc, v4, v5
	v_readlane_b32 s16, v255, 15
	s_add_i32 s1, 0, 0x1a000
	v_cndmask_b32_e32 v4, v4, v224, vcc
	v_lshlrev_b32_e32 v247, 2, v4
	v_subrev_u32_e32 v4, 32, v224
	v_cmp_lt_i32_e32 vcc, v4, v5
	v_and_b32_e32 v218, 0x78, v16
	v_and_b32_e32 v204, 12, v17
	v_cndmask_b32_e32 v4, v4, v224, vcc
	v_lshlrev_b32_e32 v248, 2, v4
	v_bfrev_b32_e32 v4, 0.5
	v_add_u32_e32 v221, s0, v15
	v_readlane_b32 s0, v255, 18
	v_lshl_or_b32 v249, v224, 2, v4
	v_lshl_add_u64 v[4:5], s[12:13], 0, v[188:189]
	v_lshlrev_b32_e32 v188, 4, v12
	v_mul_lo_u32 v10, v203, s34
	v_add_u32_e32 v210, s16, v6
	v_add_u32_e32 v211, s1, v6
	v_lshlrev_b32_e32 v6, 2, v12
	v_lshlrev_b32_e32 v212, 3, v12
	v_add_u32_e32 v214, s16, v15
	v_add_u32_e32 v215, 0, v213
	v_mul_u32_u24_e32 v16, 0x110, v218
	v_add_u32_e32 v222, s0, v15
	v_add_u32_e32 v13, 0, v13
	v_lshlrev_b32_e32 v15, 1, v204
	v_lshl_add_u64 v[206:207], v[4:5], 0, v[188:189]
	v_mul_u32_u24_e32 v4, 0x110, v19
	s_mov_b32 s0, 0x8800
	v_or_b32_e32 v201, 0x200, v199
	v_and_b32_e32 v198, 56, v199
	v_add_u32_e32 v205, -2, v203
	v_add_u32_e32 v219, -2, v218
	s_or_b32 s16, s5, 15
	v_add3_u32 v250, 0, v4, v212
	v_mov_b32_e32 v191, v202
	v_mad_u32_u24 v251, v17, s34, v18
	v_add3_u32 v252, v216, v213, s0
	v_add_u32_e32 v232, v9, v10
	v_add_u32_e32 v225, v9, v11
	v_lshlrev_b32_e32 v208, 2, v6
	v_add_u32_e32 v228, v14, v213
	v_add_u32_e32 v229, v215, v7
	v_add_u32_e32 v230, v8, v16
	v_add_u32_e32 v231, v13, v15
	v_readlane_b32 s2, v255, 40
	s_nop 4
	s_branch .LBB0_473
